# N9 + priorities swapped: the MFMA-bound non-producing wave at priority 2, the softmax-producing wave at 0
# speedup vs baseline: 1.0310x; 1.0100x over previous
; #define SBAR() __builtin_amdgcn_sched_barrier(0)
; #define KLOAD(k0) do { ks0 = *reinterpret_cast<const bf16x8*>(&Kh[(long)((k0) + sr) * LDK + sc]); ks1 = *reinterpret_cast<const bf16x8*>(&Kh[(long)((k0) + 32 + sr) * LDK + sc]); } while (0)
; #define VLOAD(k0) do { vs00 = *reinterpret_cast<const bf16x8*>(&Vh[(long)((k0) + sr) * LDK + sc]); vs01 = *reinterpret_cast<const bf16x8*>(&Vh[(long)((k0) + 32 + sr) * LDK + sc]); \
;     vs10 = *reinterpret_cast<const bf16x8*>(&Vh[(long)((k0) + sr) * LDK + 128 + sc]); vs11 = *reinterpret_cast<const bf16x8*>(&Vh[(long)((k0) + 32 + sr) * LDK + 128 + sc]); } while (0)
; #define KWRITE(b) do { const int kc = sc * 2; *(bf16x8*)(K_lds + (b) * 16384 + KSWZ(sr, kc)) = ks0; *(bf16x8*)(K_lds + (b) * 16384 + KSWZ(32 + sr, kc)) = ks1; } while (0)
; #define VWRITE(b) do { *(bf16x8*)(V_lds + (b) * 32768 + vst0) = vs00; *(bf16x8*)(V_lds + (b) * 32768 + vst1) = vs01; \
;     *(bf16x8*)(V_lds + (b) * 32768 + 16384 + vst0) = vs10; *(bf16x8*)(V_lds + (b) * 32768 + 16384 + vst1) = vs11; } while (0)
; template <int LDQ, int LDK, int LDO>
; __device__ __forceinline__ void attn_pair_body(const bf16* __restrict__ Qb, const bf16* __restrict__ Kh, const bf16* __restrict__ Vh, float* __restrict__ Ob, int NT, char* lds, int tid_in) {
;     ...
;   for (int j = 0; j <= NT; ++j) {
;     const int b = j & 1, pb = b ^ 1;
;     const bool prod = (j < NT) && (b == vhw);
;     if (prod) __builtin_amdgcn_s_setprio(2); else __builtin_amdgcn_s_setprio(0);
;     const bool flp = (j >= 1) && (__builtin_amdgcn_readfirstlane((int)FLp[pb]) != 0);
;     const float alp_v = ALp[pb * 32 + r32], m_v = Mp[r32];
;     const bf16x8 a0 = *reinterpret_cast<const bf16x8*>(Pp + pb * 4096 + 0 * 1024 + lane * 16), a1 = *reinterpret_cast<const bf16x8*>(Pp + pb * 4096 + 1 * 1024 + lane * 16);
;     const bf16x8 a2 = *reinterpret_cast<const bf16x8*>(Pp + pb * 4096 + 2 * 1024 + lane * 16), a3 = *reinterpret_cast<const bf16x8*>(Pp + pb * 4096 + 3 * 1024 + lane * 16);
;     SBAR();
;     KWRITE(b);
;     VWRITE(b);
;     { const int tk = j + 3 < NT ? j + 3 : NT - 1, tv = j + 1 < NT ? j + 1 : NT - 1; KLOAD(tk * KVBLK); VLOAD(tv * KVBLK); }
;     SBAR();
;     if (prod) {
;       if (flp) l_reg *= alp_v;
;       if (j >= 1) m_reg = m_v;
;       float mn, al; bf16x8 pa0, pa1, pa2, pa3;
;       partialSM(p0, p1, m_reg, mn, al);
.Lpa_hdr:
	s_add_i32 s15, s11, -1
	s_and_b32 s28, s15, 1
	s_xor_b32 s21, s28, 1
	s_lshl_b32 s29, s21, 2
	s_add_i32 s29, s10, s29
	v_mov_b32_e32 v210, s29
	v_lshl_add_u32 v157, s21, 12, v216
	v_lshl_add_u32 v156, s21, 7, v214
	s_cmp_lg_u32 s15, 0
	s_cselect_b64 s[56:57], -1, 0
	s_cselect_b64 s[44:45], 0, -1
	s_cmp_eq_u32 s28, s8
	s_cselect_b64 s[52:53], -1, 0
	s_cmp_lt_i32 s15, s4
	s_cselect_b64 s[42:43], -1, 0
	s_and_b64 s[42:43], s[42:43], s[52:53]
	s_waitcnt vmcnt(0) lgkmcnt(0)
	s_barrier
	s_cbranch_scc0 .Lpa_cons
	s_setprio 0
	ds_read_b32 v210, v210
	ds_read_b32 v219, v156
	ds_read_b32 v220, v212
	s_xor_b32 s65, s65, 0x4000
	s_xor_b32 s77, s77, 0x8000
	s_add_u32 s74, s74, 0x90000
	s_addc_u32 s75, s75, 0
	s_add_u32 s92, s92, 0x90000
	s_addc_u32 s93, s93, 0
	s_add_u32 s96, s96, 0x90000
	s_addc_u32 s97, s97, 0
	s_mov_b32 m0, s65
	v_max_f32_e32 v176, v85, v85
	v_max_f32_e32 v177, v84, v84
	global_load_lds_dwordx4 v172, s[74:75]
	s_add_i32 m0, s65, 0x400
	v_max_f32_e32 v176, v177, v176
	v_max3_f32 v176, v176, v86, v87
	v_max3_f32 v176, v176, v88, v89
	v_max3_f32 v176, v176, v90, v91
	v_max3_f32 v176, v176, v92, v93
	v_max3_f32 v176, v176, v94, v95
	v_max3_f32 v176, v176, v96, v97
	v_max3_f32 v176, v176, v98, v99
	global_load_lds_dwordx4 v173, s[74:75]
	s_mov_b32 m0, s77
	v_max3_f32 v176, v176, v68, v69
	v_max3_f32 v176, v176, v70, v71
	v_max3_f32 v176, v176, v72, v73
	v_max3_f32 v176, v176, v74, v75
	v_max3_f32 v176, v176, v76, v77
	v_max3_f32 v176, v176, v78, v79
	v_max3_f32 v176, v176, v80, v81
	v_max3_f32 v176, v176, v82, v83
	global_load_lds_dwordx4 v174, s[92:93]
	s_add_i32 m0, s77, 0x380
	v_mov_b32_e32 v177, v176
	s_nop 1
	v_permlane32_swap_b32_e32 v176, v177
	v_max_f32_e32 v177, v177, v177
	v_max_f32_e32 v176, v176, v176
	s_waitcnt lgkmcnt(0)
	v_readfirstlane_b32 s29, v210
	s_cmp_lg_u32 s29, 0
	s_cselect_b64 s[62:63], -1, 0
	s_and_b64 s[62:63], s[62:63], s[56:57]
	v_cndmask_b32_e64 v217, v220, v217, s[44:45]
	v_max_f32_e32 v221, v176, v177
	v_sub_f32_e32 v176, v221, v217
	v_cmp_ge_f32_e32 vcc, s27, v176
	s_cmp_eq_u64 vcc, exec
	v_mov_b32_e32 v220, 1.0
	s_cbranch_scc0 .LBB0_1036

; #define SBAR() __builtin_amdgcn_sched_barrier(0)
; __device__ __forceinline__ int crow(int r, int hi) { return (r & 3) + 8 * (r >> 2) + 4 * hi; }
; template <int LDQ, int LDK, int LDO>
; __device__ __forceinline__ void attn_pair_body(const bf16* __restrict__ Qb, const bf16* __restrict__ Kh, const bf16* __restrict__ Vh, float* __restrict__ Ob, int NT, char* lds, int tid_in) {
;     ...
;     if (j >= 1) {
;       if (flp) {
; #pragma unroll
;         for (int d = 0; d < 4; ++d)
; #pragma unroll
;           for (int r = 0; r < 16; ++r) o[d][r] *= ALp[pb * 32 + crow(r, hi)];
;       }
;       pv_batched(o, vb0 + pb * 32768, a0, a1, a2, a3);
;     }
;     if (!prod && j + 1 < NT) { SBAR(); qkt_batched(p0, p1, (const bf16*)(K_lds + pb * 16384), qr, r32, hi); SBAR(); }
.Lpa_cons:
	s_setprio 2
	ds_read_b32 v210, v210
	ds_read_b128 v[168:171], v157
	ds_read_b128 v[164:167], v157 offset:1024
	ds_read_b128 v[160:163], v157 offset:2048
	ds_read_b128 v[156:159], v157 offset:3072
	v_lshl_add_u32 v219, s21, 15, v211
	ds_read_b64_tr_b16 v[220:221], v219 offset:0
	ds_read_b64_tr_b16 v[222:223], v219 offset:0x800
	ds_read_b64_tr_b16 v[224:225], v219 offset:0x1000
	ds_read_b64_tr_b16 v[226:227], v219 offset:0x1800
	ds_read_b64_tr_b16 v[234:235], v219 offset:0x2000
	ds_read_b64_tr_b16 v[236:237], v219 offset:0x2800
	ds_read_b64_tr_b16 v[238:239], v219 offset:0x3000
	ds_read_b64_tr_b16 v[240:241], v219 offset:0x3800
	ds_read_b64_tr_b16 v[242:243], v219 offset:0x200
	ds_read_b64_tr_b16 v[244:245], v219 offset:0xa00
	ds_read_b64_tr_b16 v[246:247], v219 offset:0x1200
	ds_read_b64_tr_b16 v[248:249], v219 offset:0x1a00
	ds_read_b64_tr_b16 v[176:177], v219 offset:0x2200
	ds_read_b64_tr_b16 v[178:179], v219 offset:0x2a00
	ds_read_b64_tr_b16 v[228:229], v219 offset:0x3200
	ds_read_b64_tr_b16 v[230:231], v219 offset:0x3a00
	s_waitcnt lgkmcnt(15)
	v_readfirstlane_b32 s29, v210
	s_cmp_lg_u32 s29, 0
	s_cselect_b64 s[62:63], -1, 0
	s_and_b64 s[62:63], s[62:63], s[56:57]
	s_andn2_b64 vcc, exec, s[56:57]
	s_cbranch_vccnz .Lpa_cons_j0
	s_lshl_b32 s28, s21, 5
	s_andn2_b64 vcc, exec, s[62:63]
	s_cbranch_vccnz .Lpa_cons_pv
	v_lshl_add_u32 v148, s28, 2, v215
	ds_read_b128 v[132:135], v148 offset:96
	ds_read_b128 v[136:139], v148 offset:64
	ds_read_b128 v[140:143], v148 offset:32
	ds_read_b128 v[144:147], v148
	s_waitcnt lgkmcnt(3)
	v_pk_mul_f32 v[18:19], v[18:19], v[134:135]
	s_waitcnt lgkmcnt(2)
	v_pk_mul_f32 v[14:15], v[14:15], v[138:139]
	s_waitcnt lgkmcnt(1)
	v_pk_mul_f32 v[10:11], v[10:11], v[142:143]
	s_waitcnt lgkmcnt(0)
	v_pk_mul_f32 v[6:7], v[6:7], v[146:147]
	v_pk_mul_f32 v[16:17], v[16:17], v[132:133]
	v_pk_mul_f32 v[12:13], v[12:13], v[136:137]
	v_pk_mul_f32 v[8:9], v[8:9], v[140:141]
	v_pk_mul_f32 v[4:5], v[4:5], v[144:145]
	v_pk_mul_f32 v[66:67], v[66:67], v[134:135]
	v_pk_mul_f32 v[62:63], v[62:63], v[138:139]
	v_pk_mul_f32 v[58:59], v[58:59], v[142:143]
	v_pk_mul_f32 v[54:55], v[54:55], v[146:147]
	v_pk_mul_f32 v[64:65], v[64:65], v[132:133]
	v_pk_mul_f32 v[60:61], v[60:61], v[136:137]
	v_pk_mul_f32 v[56:57], v[56:57], v[140:141]
	v_pk_mul_f32 v[52:53], v[52:53], v[144:145]
	v_pk_mul_f32 v[50:51], v[50:51], v[134:135]
	v_pk_mul_f32 v[46:47], v[46:47], v[138:139]
	v_pk_mul_f32 v[42:43], v[42:43], v[142:143]
	v_pk_mul_f32 v[38:39], v[38:39], v[146:147]
	v_pk_mul_f32 v[48:49], v[48:49], v[132:133]
	v_pk_mul_f32 v[44:45], v[44:45], v[136:137]
	v_pk_mul_f32 v[40:41], v[40:41], v[140:141]
	v_pk_mul_f32 v[36:37], v[36:37], v[144:145]
	v_pk_mul_f32 v[34:35], v[34:35], v[134:135]
	v_pk_mul_f32 v[30:31], v[30:31], v[138:139]
	v_pk_mul_f32 v[26:27], v[26:27], v[142:143]
	v_pk_mul_f32 v[22:23], v[22:23], v[146:147]
	v_pk_mul_f32 v[32:33], v[32:33], v[132:133]
	v_pk_mul_f32 v[28:29], v[28:29], v[136:137]
	v_pk_mul_f32 v[24:25], v[24:25], v[140:141]
	v_pk_mul_f32 v[20:21], v[20:21], v[144:145]
